# lever 4 variant: attention A keeps the PV priority raise only for hw waves 4-7 (waves 0-3 PV priority flips removed)
# speedup vs baseline: 1.0022x; 1.0022x over previous
; __device__ __forceinline__ unsigned cvt_pk_bf16(float lo, float hi) { unsigned r; asm volatile("v_cvt_pk_bf16_f32 %0, %1, %2" : "=v"(r) : "v"(lo), "v"(hi)); return r; }
; __device__ __forceinline__ float fast_exp2(float x) { return __builtin_amdgcn_exp2f(x); }
; template <int MODE>
; __device__ void attn_block(LAS unsigned char* lds, const bf16_t* Qp, const bf16_t* Kp, const bf16_t* Vp, int qb, const unsigned* maskp, const bf16_t* sga, bf16_t* outp, const float negMB) {
;     ...
; #pragma unroll
;             for (int r = 0; r < 16; ++r) { s0[r] = fast_exp2(s0[r]); s1[r] = fast_exp2(s1[r]); }
;             if (MODE == 0) {
; #pragma unroll
;                 for (int r = 0; r < 16; ++r) { const int bit = (r & 3) + 8 * (r >> 2) + 4 * h;
;                     const int m0 = __builtin_amdgcn_sbfe((int)mw.x, bit, 1), m1 = __builtin_amdgcn_sbfe((int)mw.y, bit, 1);
;                     s0[r] = __int_as_float(__float_as_int(s0[r]) & m0); s1[r] = __int_as_float(__float_as_int(s1[r]) & m1); }
;             }
;             float ls = 0.f;
; #pragma unroll
;             for (int r = 0; r < 16; ++r) ls += s0[r] + s1[r];
;             lrun += ls;
; #pragma unroll
;             for (int s2 = 0; s2 < 2; ++s2) {
;                 u32x4 w0, w1;
;                 w0.x = cvt_pk_bf16(s0[8 * s2 + 0], s0[8 * s2 + 1]); w0.y = cvt_pk_bf16(s0[8 * s2 + 2], s0[8 * s2 + 3]); w0.z = cvt_pk_bf16(s0[8 * s2 + 4], s0[8 * s2 + 5]); w0.w = cvt_pk_bf16(s0[8 * s2 + 6], s0[8 * s2 + 7]);
;                 w1.x = cvt_pk_bf16(s1[8 * s2 + 0], s1[8 * s2 + 1]); w1.y = cvt_pk_bf16(s1[8 * s2 + 2], s1[8 * s2 + 3]); w1.z = cvt_pk_bf16(s1[8 * s2 + 4], s1[8 * s2 + 5]); w1.w = cvt_pk_bf16(s1[8 * s2 + 6], s1[8 * s2 + 7]);
;                 pf[0][s2] = __builtin_bit_cast(bf16x8, w0); pf[1][s2] = __builtin_bit_cast(bf16x8, w1);
;             }
;             if (grp == 0) ATT_PV(sj);
.LBB0_852:
	v_exp_f32_e32 v32, v32
	v_exp_f32_e32 v33, v33
	s_nop 6
	v_exp_f32_e32 v48, v48
	v_exp_f32_e32 v34, v34
	v_exp_f32_e32 v50, v50
	v_or_b32_e32 v192, 1, v168
	v_exp_f32_e32 v49, v49
	v_exp_f32_e32 v35, v35
	v_exp_f32_e32 v51, v51
	s_waitcnt vmcnt(0)
	v_bfe_i32 v78, v156, v168, 1
	v_exp_f32_e32 v36, v36
	v_exp_f32_e32 v52, v52
	v_exp_f32_e32 v37, v37
	v_exp_f32_e32 v53, v53
	v_exp_f32_e32 v38, v38
	v_exp_f32_e32 v54, v54
	v_exp_f32_e32 v39, v39
	v_exp_f32_e32 v55, v55
	v_exp_f32_e32 v40, v40
	v_exp_f32_e32 v56, v56
	v_exp_f32_e32 v41, v41
	v_exp_f32_e32 v57, v57
	v_exp_f32_e32 v42, v42
	v_exp_f32_e32 v58, v58
	v_exp_f32_e32 v43, v43
	v_exp_f32_e32 v59, v59
	v_exp_f32_e32 v44, v44
	v_exp_f32_e32 v60, v60
	v_exp_f32_e32 v45, v45
	v_exp_f32_e32 v61, v61
	v_exp_f32_e32 v46, v46
	v_exp_f32_e32 v62, v62
	v_exp_f32_e32 v47, v47
	v_exp_f32_e32 v63, v63
	v_and_b32_e32 v193, v78, v32
	v_bfe_i32 v32, v156, v192, 1
	v_bfe_i32 v79, v157, v168, 1
	v_and_b32_e32 v198, v32, v33
	v_bfe_i32 v32, v156, v64, 1
	v_bfe_i32 v33, v157, v64, 1
	v_and_b32_e32 v197, v79, v48
	v_bfe_i32 v48, v157, v192, 1
	v_and_b32_e32 v200, v32, v34
	v_and_b32_e32 v201, v33, v50
	v_bfe_i32 v32, v156, v65, 1
	v_bfe_i32 v33, v157, v65, 1
	v_and_b32_e32 v199, v48, v49
	v_and_b32_e32 v202, v32, v35
	v_and_b32_e32 v203, v33, v51
	v_bfe_i32 v32, v156, v66, 1
	v_bfe_i32 v33, v157, v66, 1
	v_bfe_i32 v34, v156, v67, 1
	v_bfe_i32 v35, v157, v67, 1
	v_bfe_i32 v48, v156, v68, 1
	v_bfe_i32 v49, v157, v68, 1
	v_bfe_i32 v50, v156, v69, 1
	v_bfe_i32 v51, v157, v69, 1
	v_bfe_i32 v64, v156, v70, 1
	v_bfe_i32 v65, v157, v70, 1
	v_bfe_i32 v66, v156, v71, 1
	v_bfe_i32 v67, v157, v71, 1
	v_bfe_i32 v68, v156, v72, 1
	v_bfe_i32 v69, v157, v72, 1
	v_bfe_i32 v70, v156, v73, 1
	v_bfe_i32 v71, v157, v73, 1
	v_bfe_i32 v72, v156, v74, 1
	v_bfe_i32 v73, v157, v74, 1
	v_bfe_i32 v74, v156, v75, 1
	v_bfe_i32 v75, v157, v75, 1
	v_bfe_i32 v78, v156, v76, 1
	v_bfe_i32 v76, v157, v76, 1
	v_bfe_i32 v79, v156, v77, 1
	v_bfe_i32 v77, v157, v77, 1
	v_and_b32_e32 v113, v32, v36
	v_and_b32_e32 v112, v34, v37
	v_and_b32_e32 v115, v33, v52
	v_and_b32_e32 v114, v35, v53
	v_and_b32_e32 v117, v48, v38
	v_and_b32_e32 v116, v50, v39
	v_and_b32_e32 v119, v49, v54
	v_and_b32_e32 v118, v51, v55
	v_and_b32_e32 v121, v64, v40
	v_and_b32_e32 v120, v66, v41
	v_and_b32_e32 v123, v65, v56
	v_and_b32_e32 v122, v67, v57
	v_and_b32_e32 v125, v68, v42
	v_and_b32_e32 v124, v70, v43
	v_and_b32_e32 v127, v69, v58
	v_and_b32_e32 v126, v71, v59
	v_and_b32_e32 v177, v72, v44
	v_and_b32_e32 v176, v74, v45
	v_and_b32_e32 v179, v73, v60
	v_and_b32_e32 v178, v75, v61
	v_and_b32_e32 v181, v78, v46
	v_and_b32_e32 v180, v79, v47
	v_and_b32_e32 v183, v76, v62
	v_and_b32_e32 v182, v77, v63
	s_andn2_b64 vcc, exec, s[4:5]
	v_cvt_pk_bf16_f32 v104, v193, v198
	v_cvt_pk_bf16_f32 v105, v200, v202
	v_cvt_pk_bf16_f32 v106, v113, v112
	v_cvt_pk_bf16_f32 v107, v117, v116
	v_cvt_pk_bf16_f32 v100, v197, v199
	v_cvt_pk_bf16_f32 v101, v201, v203
	v_cvt_pk_bf16_f32 v102, v115, v114
	v_cvt_pk_bf16_f32 v103, v119, v118
	v_cvt_pk_bf16_f32 v108, v121, v120
	v_cvt_pk_bf16_f32 v109, v125, v124
	v_cvt_pk_bf16_f32 v110, v177, v176
	v_cvt_pk_bf16_f32 v111, v181, v180
	v_cvt_pk_bf16_f32 v96, v123, v122
	v_cvt_pk_bf16_f32 v97, v127, v126
	v_cvt_pk_bf16_f32 v98, v179, v178
	v_cvt_pk_bf16_f32 v99, v183, v182
	s_cbranch_vccnz .LBB0_854
	v_add_u32_e32 v212, 0, v187
	ds_read_b64_tr_b16 v[32:33], v212 offset:17408
	ds_read_b64_tr_b16 v[34:35], v212 offset:19968
	ds_read_b64_tr_b16 v[36:37], v212 offset:17472
	ds_read_b64_tr_b16 v[38:39], v212 offset:20032
	ds_read_b64_tr_b16 v[40:41], v212 offset:17536
	ds_read_b64_tr_b16 v[42:43], v212 offset:20096
	s_waitcnt lgkmcnt(4)
	v_mfma_f32_32x32x16_bf16 v[80:95], v[32:35], v[104:107], 0
	ds_read_b64_tr_b16 v[32:33], v212 offset:17600
	ds_read_b64_tr_b16 v[34:35], v212 offset:20160
	s_waitcnt lgkmcnt(4)
	v_mfma_f32_32x32x16_bf16 v[64:79], v[36:39], v[104:107], 0
	ds_read_b64_tr_b16 v[204:205], v212 offset:22528
	ds_read_b64_tr_b16 v[206:207], v212 offset:25088
	s_waitcnt lgkmcnt(4)
	v_mfma_f32_32x32x16_bf16 v[48:63], v[40:43], v[104:107], 0
	ds_read_b64_tr_b16 v[208:209], v212 offset:22592
	ds_read_b64_tr_b16 v[210:211], v212 offset:25152
	s_waitcnt lgkmcnt(4)
	v_mfma_f32_32x32x16_bf16 v[32:47], v[32:35], v[104:107], 0
	ds_read_b64_tr_b16 v[216:217], v212 offset:22656
	ds_read_b64_tr_b16 v[218:219], v212 offset:25216
	s_waitcnt lgkmcnt(4)
	v_mfma_f32_32x32x16_bf16 v[80:95], v[204:207], v[108:111], v[80:95]
	ds_read_b64_tr_b16 v[204:205], v212 offset:22720
	ds_read_b64_tr_b16 v[206:207], v212 offset:25280
	s_waitcnt lgkmcnt(4)
	v_mfma_f32_32x32x16_bf16 v[64:79], v[208:211], v[108:111], v[64:79]
	ds_read_b64_tr_b16 v[208:209], v212 offset:27648
	ds_read_b64_tr_b16 v[210:211], v212 offset:30208
	s_waitcnt lgkmcnt(4)
	v_mfma_f32_32x32x16_bf16 v[48:63], v[216:219], v[108:111], v[48:63]
	ds_read_b64_tr_b16 v[216:217], v212 offset:27712
	ds_read_b64_tr_b16 v[218:219], v212 offset:30272
	s_waitcnt lgkmcnt(4)
	v_mfma_f32_32x32x16_bf16 v[32:47], v[204:207], v[108:111], v[32:47]
	ds_read_b64_tr_b16 v[204:205], v212 offset:27776
	ds_read_b64_tr_b16 v[206:207], v212 offset:30336
	s_waitcnt lgkmcnt(4)
	v_mfma_f32_32x32x16_bf16 v[80:95], v[208:211], v[100:103], v[80:95]
	ds_read_b64_tr_b16 v[208:209], v212 offset:27840
	ds_read_b64_tr_b16 v[210:211], v212 offset:30400
	s_waitcnt lgkmcnt(4)
	v_mfma_f32_32x32x16_bf16 v[64:79], v[216:219], v[100:103], v[64:79]
	ds_read_b64_tr_b16 v[216:217], v212 offset:32768
	ds_read_b64_tr_b16 v[218:219], v212 offset:35328
	s_waitcnt lgkmcnt(4)
	v_mfma_f32_32x32x16_bf16 v[48:63], v[204:207], v[100:103], v[48:63]
	ds_read_b64_tr_b16 v[204:205], v212 offset:32832
	ds_read_b64_tr_b16 v[206:207], v212 offset:35392
	s_waitcnt lgkmcnt(4)
	v_mfma_f32_32x32x16_bf16 v[32:47], v[208:211], v[100:103], v[32:47]
	ds_read_b64_tr_b16 v[208:209], v212 offset:32896
	ds_read_b64_tr_b16 v[210:211], v212 offset:35456
	s_waitcnt lgkmcnt(4)
	v_mfma_f32_32x32x16_bf16 v[80:95], v[216:219], v[96:99], v[80:95]
	ds_read_b64_tr_b16 v[216:217], v212 offset:32960
	ds_read_b64_tr_b16 v[218:219], v212 offset:35520
	s_waitcnt lgkmcnt(4)
	v_mfma_f32_32x32x16_bf16 v[64:79], v[204:207], v[96:99], v[64:79]
	s_waitcnt lgkmcnt(2)
	v_mfma_f32_32x32x16_bf16 v[48:63], v[208:211], v[96:99], v[48:63]
	s_waitcnt lgkmcnt(0)
	v_mfma_f32_32x32x16_bf16 v[32:47], v[216:219], v[96:99], v[32:47]
	s_branch .LBB0_855

; __device__ __forceinline__ unsigned cvt_pk_bf16(float lo, float hi) { unsigned r; asm volatile("v_cvt_pk_bf16_f32 %0, %1, %2" : "=v"(r) : "v"(lo), "v"(hi)); return r; }
; __device__ __forceinline__ float fast_exp2(float x) { return __builtin_amdgcn_exp2f(x); }
; template <int MODE>
; __device__ void attn_block(LAS unsigned char* lds, const bf16_t* Qp, const bf16_t* Kp, const bf16_t* Vp, int qb, const unsigned* maskp, const bf16_t* sga, bf16_t* outp, const float negMB) {
;     ...
; #pragma unroll
;             for (int r = 0; r < 16; ++r) { s0[r] = fast_exp2(s0[r]); s1[r] = fast_exp2(s1[r]); }
;             if (MODE == 0) {
; #pragma unroll
;                 for (int r = 0; r < 16; ++r) { const int bit = (r & 3) + 8 * (r >> 2) + 4 * h;
;                     const int m0 = __builtin_amdgcn_sbfe((int)mw.x, bit, 1), m1 = __builtin_amdgcn_sbfe((int)mw.y, bit, 1);
;                     s0[r] = __int_as_float(__float_as_int(s0[r]) & m0); s1[r] = __int_as_float(__float_as_int(s1[r]) & m1); }
;             }
;             float ls = 0.f;
; #pragma unroll
;             for (int r = 0; r < 16; ++r) ls += s0[r] + s1[r];
;             lrun += ls;
; #pragma unroll
;             for (int s2 = 0; s2 < 2; ++s2) {
;                 u32x4 w0, w1;
;                 w0.x = cvt_pk_bf16(s0[8 * s2 + 0], s0[8 * s2 + 1]); w0.y = cvt_pk_bf16(s0[8 * s2 + 2], s0[8 * s2 + 3]); w0.z = cvt_pk_bf16(s0[8 * s2 + 4], s0[8 * s2 + 5]); w0.w = cvt_pk_bf16(s0[8 * s2 + 6], s0[8 * s2 + 7]);
;                 w1.x = cvt_pk_bf16(s1[8 * s2 + 0], s1[8 * s2 + 1]); w1.y = cvt_pk_bf16(s1[8 * s2 + 2], s1[8 * s2 + 3]); w1.z = cvt_pk_bf16(s1[8 * s2 + 4], s1[8 * s2 + 5]); w1.w = cvt_pk_bf16(s1[8 * s2 + 6], s1[8 * s2 + 7]);
;                 pf[0][s2] = __builtin_bit_cast(bf16x8, w0); pf[1][s2] = __builtin_bit_cast(bf16x8, w1);
;             }
;             if (grp == 0) ATT_PV(sj);
.Lma_odd:
	s_nop 4
	v_exp_f32_e32 v96, v96
	v_exp_f32_e32 v97, v97
	v_exp_f32_e32 v98, v98
	s_nop 2
	v_exp_f32_e32 v114, v114
	v_exp_f32_e32 v112, v112
	v_exp_f32_e32 v99, v99
	v_exp_f32_e32 v115, v115
	v_exp_f32_e32 v178, v119
	v_bfe_i32 v119, v177, v168, 1
	v_exp_f32_e32 v113, v113
	v_exp_f32_e32 v100, v100
	v_exp_f32_e32 v116, v116
	v_exp_f32_e32 v101, v101
	v_exp_f32_e32 v117, v117
	v_exp_f32_e32 v102, v102
	v_exp_f32_e32 v118, v118
	v_exp_f32_e32 v103, v103
	v_exp_f32_e32 v104, v104
	v_exp_f32_e32 v179, v120
	v_exp_f32_e32 v105, v105
	v_exp_f32_e32 v180, v121
	v_exp_f32_e32 v106, v106
	v_exp_f32_e32 v181, v122
	v_exp_f32_e32 v107, v107
	v_exp_f32_e32 v182, v123
	v_exp_f32_e32 v108, v108
	v_exp_f32_e32 v183, v124
	v_exp_f32_e32 v109, v109
	v_exp_f32_e32 v218, v125
	v_exp_f32_e32 v110, v110
	v_exp_f32_e32 v219, v126
	v_exp_f32_e32 v111, v111
	v_exp_f32_e32 v220, v127
	v_and_b32_e32 v209, v119, v96
	v_bfe_i32 v96, v177, v192, 1
	v_and_b32_e32 v211, v96, v97
	v_bfe_i32 v96, v177, v194, 1
	v_bfe_i32 v97, v176, v194, 1
	v_bfe_i32 v120, v176, v168, 1
	v_and_b32_e32 v213, v96, v98
	v_and_b32_e32 v215, v97, v114
	v_bfe_i32 v96, v177, v195, 1
	v_bfe_i32 v97, v176, v195, 1
	v_and_b32_e32 v210, v120, v112
	v_bfe_i32 v112, v176, v192, 1
	v_and_b32_e32 v216, v96, v99
	v_and_b32_e32 v217, v97, v115
	v_bfe_i32 v96, v177, v196, 1
	v_bfe_i32 v97, v176, v196, 1
	v_bfe_i32 v98, v177, v197, 1
	v_bfe_i32 v99, v176, v197, 1
	v_bfe_i32 v119, v177, v198, 1
	v_bfe_i32 v120, v176, v198, 1
	v_bfe_i32 v121, v177, v199, 1
	v_bfe_i32 v122, v176, v199, 1
	v_bfe_i32 v123, v177, v200, 1
	v_bfe_i32 v124, v176, v200, 1
	v_bfe_i32 v125, v177, v201, 1
	v_bfe_i32 v126, v176, v201, 1
	v_bfe_i32 v127, v177, v202, 1
	v_bfe_i32 v221, v176, v202, 1
	v_bfe_i32 v222, v177, v203, 1
	v_bfe_i32 v223, v176, v203, 1
	v_bfe_i32 v224, v177, v204, 1
	v_bfe_i32 v225, v176, v204, 1
	v_bfe_i32 v226, v177, v205, 1
	v_bfe_i32 v227, v176, v205, 1
	v_bfe_i32 v228, v177, v206, 1
	v_bfe_i32 v229, v176, v206, 1
	v_bfe_i32 v230, v177, v207, 1
	v_bfe_i32 v231, v176, v207, 1
	v_and_b32_e32 v212, v112, v113
	v_and_b32_e32 v113, v96, v100
	v_and_b32_e32 v112, v98, v101
	v_and_b32_e32 v115, v97, v116
	v_and_b32_e32 v114, v99, v117
	v_and_b32_e32 v117, v119, v102
	v_and_b32_e32 v116, v121, v103
	v_and_b32_e32 v119, v120, v118
	v_and_b32_e32 v118, v122, v178
	v_and_b32_e32 v121, v123, v104
	v_and_b32_e32 v120, v125, v105
	v_and_b32_e32 v123, v124, v179
	v_and_b32_e32 v122, v126, v180
	v_and_b32_e32 v125, v127, v106
	v_and_b32_e32 v124, v222, v107
	v_and_b32_e32 v127, v221, v181
	v_and_b32_e32 v126, v223, v182
	v_and_b32_e32 v177, v224, v108
	v_and_b32_e32 v176, v226, v109
	v_and_b32_e32 v179, v225, v183
	v_and_b32_e32 v178, v227, v218
	v_and_b32_e32 v181, v228, v110
	v_and_b32_e32 v180, v230, v111
	v_and_b32_e32 v183, v229, v219
	v_and_b32_e32 v182, v231, v220
	s_andn2_b64 vcc, exec, s[4:5]
	v_cvt_pk_bf16_f32 v104, v209, v211
	v_cvt_pk_bf16_f32 v105, v213, v216
	v_cvt_pk_bf16_f32 v106, v113, v112
	v_cvt_pk_bf16_f32 v107, v117, v116
	v_cvt_pk_bf16_f32 v100, v210, v212
	v_cvt_pk_bf16_f32 v101, v215, v217
	v_cvt_pk_bf16_f32 v102, v115, v114
	v_cvt_pk_bf16_f32 v103, v119, v118
	v_cvt_pk_bf16_f32 v108, v121, v120
	v_cvt_pk_bf16_f32 v109, v125, v124
	v_cvt_pk_bf16_f32 v110, v177, v176
	v_cvt_pk_bf16_f32 v111, v181, v180
	v_cvt_pk_bf16_f32 v96, v123, v122
	v_cvt_pk_bf16_f32 v97, v127, v126
	v_cvt_pk_bf16_f32 v98, v179, v178
	v_cvt_pk_bf16_f32 v99, v183, v182
	s_cbranch_vccnz .LBB0_874
	v_add_u32_e32 v230, s8, v187
	ds_read_b64_tr_b16 v[218:219], v230 offset:17408
	ds_read_b64_tr_b16 v[220:221], v230 offset:19968
	ds_read_b64_tr_b16 v[222:223], v230 offset:17472
	ds_read_b64_tr_b16 v[224:225], v230 offset:20032
	ds_read_b64_tr_b16 v[226:227], v230 offset:17536
	ds_read_b64_tr_b16 v[228:229], v230 offset:20096
	s_waitcnt lgkmcnt(4)
	v_mfma_f32_32x32x16_bf16 v[80:95], v[218:221], v[104:107], v[80:95]
	ds_read_b64_tr_b16 v[218:219], v230 offset:17600
	ds_read_b64_tr_b16 v[220:221], v230 offset:20160
	s_waitcnt lgkmcnt(4)
	v_mfma_f32_32x32x16_bf16 v[64:79], v[222:225], v[104:107], v[64:79]
	ds_read_b64_tr_b16 v[222:223], v230 offset:22528
	ds_read_b64_tr_b16 v[224:225], v230 offset:25088
	s_waitcnt lgkmcnt(4)
	v_mfma_f32_32x32x16_bf16 v[48:63], v[226:229], v[104:107], v[48:63]
	ds_read_b64_tr_b16 v[226:227], v230 offset:22592
	ds_read_b64_tr_b16 v[228:229], v230 offset:25152
	s_waitcnt lgkmcnt(4)
	v_mfma_f32_32x32x16_bf16 v[32:47], v[218:221], v[104:107], v[32:47]
	ds_read_b64_tr_b16 v[218:219], v230 offset:22656
	ds_read_b64_tr_b16 v[220:221], v230 offset:25216
	s_waitcnt lgkmcnt(4)
	v_mfma_f32_32x32x16_bf16 v[80:95], v[222:225], v[108:111], v[80:95]
	ds_read_b64_tr_b16 v[222:223], v230 offset:22720
	ds_read_b64_tr_b16 v[224:225], v230 offset:25280
	s_waitcnt lgkmcnt(4)
	v_mfma_f32_32x32x16_bf16 v[64:79], v[226:229], v[108:111], v[64:79]
	ds_read_b64_tr_b16 v[226:227], v230 offset:27648
	ds_read_b64_tr_b16 v[228:229], v230 offset:30208
	s_waitcnt lgkmcnt(4)
	v_mfma_f32_32x32x16_bf16 v[48:63], v[218:221], v[108:111], v[48:63]
	ds_read_b64_tr_b16 v[218:219], v230 offset:27712
	ds_read_b64_tr_b16 v[220:221], v230 offset:30272
	s_waitcnt lgkmcnt(4)
	v_mfma_f32_32x32x16_bf16 v[32:47], v[222:225], v[108:111], v[32:47]
	ds_read_b64_tr_b16 v[222:223], v230 offset:27776
	ds_read_b64_tr_b16 v[224:225], v230 offset:30336
	s_waitcnt lgkmcnt(4)
	v_mfma_f32_32x32x16_bf16 v[80:95], v[226:229], v[100:103], v[80:95]
	ds_read_b64_tr_b16 v[226:227], v230 offset:27840
	ds_read_b64_tr_b16 v[228:229], v230 offset:30400
	s_waitcnt lgkmcnt(4)
	v_mfma_f32_32x32x16_bf16 v[64:79], v[218:221], v[100:103], v[64:79]
	ds_read_b64_tr_b16 v[218:219], v230 offset:32768
	ds_read_b64_tr_b16 v[220:221], v230 offset:35328
	s_waitcnt lgkmcnt(4)
	v_mfma_f32_32x32x16_bf16 v[48:63], v[222:225], v[100:103], v[48:63]
	ds_read_b64_tr_b16 v[222:223], v230 offset:32832
	ds_read_b64_tr_b16 v[224:225], v230 offset:35392
	s_waitcnt lgkmcnt(4)
	v_mfma_f32_32x32x16_bf16 v[32:47], v[226:229], v[100:103], v[32:47]
	ds_read_b64_tr_b16 v[226:227], v230 offset:32896
	ds_read_b64_tr_b16 v[228:229], v230 offset:35456
	s_waitcnt lgkmcnt(4)
	v_mfma_f32_32x32x16_bf16 v[80:95], v[218:221], v[96:99], v[80:95]
	ds_read_b64_tr_b16 v[218:219], v230 offset:32960
	ds_read_b64_tr_b16 v[220:221], v230 offset:35520
	s_waitcnt lgkmcnt(4)
	v_mfma_f32_32x32x16_bf16 v[64:79], v[222:225], v[96:99], v[64:79]
	s_waitcnt lgkmcnt(2)
	v_mfma_f32_32x32x16_bf16 v[48:63], v[226:229], v[96:99], v[48:63]
	s_waitcnt lgkmcnt(0)
	v_mfma_f32_32x32x16_bf16 v[32:47], v[218:221], v[96:99], v[32:47]
